# v41: v37 + non-temporal (nt) hint on the 16 in-proj epilogue P stores
# baseline (speedup 1.0000x reference)
; DI unsigned pack2(float a, float b) { f2_t v = {a, b}; bf2_t r = __builtin_convertvector(v, bf2_t); return __builtin_bit_cast(unsigned, r); }
; template <int GP> DI void gemm_phase(const Params& p, int l, int which, char* smem, int wv) {
;     ...
;             u16* pp = p.P + (size_t)R * INW + n0 + head * 128;
;             u32x4 o;
;             o[0] = pack2(x1[0], x1[1]); o[1] = pack2(x1[2], x1[3]); o[2] = pack2(x1[4], x1[5]); o[3] = pack2(x1[6], x1[7]);
;             *(u32x4*)(pp + c1) = o;
;             o[0] = pack2(x2[0], x2[1]); o[1] = pack2(x2[2], x2[3]); o[2] = pack2(x2[4], x2[5]); o[3] = pack2(x2[6], x2[7]);
;             *(u32x4*)(pp + c2) = o;
;           }
;       }
;     }
;     if (!has_next) break;
; #pragma unroll
;     for (int a = 0; a < 2; ++a)
; #pragma unroll
;       for (int b = 0; b < 2; ++b)
; #pragma unroll
;         for (int m = 0; m < 4; ++m)
; #pragma unroll
;           for (int n = 0; n < 2; ++n) acc[a][b][m][n] = (f32x4){0.f, 0.f, 0.f, 0.f};
.LBB0_185:
	v_readlane_b32 s4, v253, 21
	v_readlane_b32 s18, v253, 35
	v_readlane_b32 s19, v253, 36
	v_readlane_b32 s5, v253, 22
	s_add_u32 s0, s74, 0xffffff00
	v_mov_b64_e32 v[146:147], s[18:19]
	v_mad_i64_i32 v[146:147], s[4:5], v178, s85, v[146:147]
	v_lshl_add_u64 v[146:147], s[44:45], 1, v[146:147]
	s_mov_b64 s[18:19], s[2:3]
	v_lshl_add_u64 v[150:151], v[146:147], 0, s[18:19]
	v_cvt_pk_bf16_f32 v146, v156, v157
	v_cvt_pk_bf16_f32 v147, v160, v161
	v_cvt_pk_bf16_f32 v148, v168, v169
	v_cvt_pk_bf16_f32 v149, v174, v175
	v_lshl_add_u64 v[150:151], v[144:145], 1, v[150:151]
	s_mov_b32 s53, s3
	s_addc_u32 s1, s75, -1
	global_store_dwordx4 v[150:151], v[146:149], off nt
	v_cvt_pk_bf16_f32 v144, v158, v159
	v_cvt_pk_bf16_f32 v145, v162, v163
	v_cvt_pk_bf16_f32 v146, v172, v173
	v_cvt_pk_bf16_f32 v147, v176, v177
	v_lshl_add_u64 v[148:149], v[150:151], 0, s[52:53]
	s_andn2_b64 vcc, exec, s[48:49]
	v_readlane_b32 s6, v253, 23
	v_readlane_b32 s7, v253, 24
	v_readlane_b32 s8, v253, 25
	v_readlane_b32 s9, v253, 26
	v_readlane_b32 s10, v253, 27
	v_readlane_b32 s11, v253, 28
	v_readlane_b32 s12, v253, 29
	v_readlane_b32 s13, v253, 30
	v_readlane_b32 s14, v253, 31
	v_readlane_b32 s15, v253, 32
	v_readlane_b32 s16, v253, 33
	v_readlane_b32 s17, v253, 34
	global_store_dwordx4 v[148:149], v[144:147], off nt
	s_cbranch_vccnz .LBB0_231
	v_mov_b32_e32 v2, 0
	s_mov_b32 s22, s38
	s_mov_b32 s24, s36
	s_mov_b64 s[26:27], s[46:47]
	s_mov_b64 s[28:29], s[40:41]
	s_mov_b32 s20, s73
	v_mov_b32_e32 v3, v2
	v_mov_b32_e32 v4, v2
	v_mov_b32_e32 v5, v2
	v_mov_b32_e32 v6, v2
	v_mov_b32_e32 v7, v2
	v_mov_b32_e32 v8, v2
	v_mov_b32_e32 v9, v2
	v_mov_b32_e32 v10, v2
	v_mov_b32_e32 v11, v2
	v_mov_b32_e32 v12, v2
	v_mov_b32_e32 v13, v2
	v_mov_b32_e32 v14, v2
	v_mov_b32_e32 v15, v2
	v_mov_b32_e32 v16, v2
	v_mov_b32_e32 v17, v2
	v_mov_b32_e32 v18, v2
	v_mov_b32_e32 v19, v2
	v_mov_b32_e32 v20, v2
	v_mov_b32_e32 v21, v2
	v_mov_b32_e32 v22, v2
	v_mov_b32_e32 v23, v2
	v_mov_b32_e32 v24, v2
	v_mov_b32_e32 v25, v2
	v_mov_b32_e32 v26, v2
	v_mov_b32_e32 v27, v2
	v_mov_b32_e32 v28, v2
	v_mov_b32_e32 v29, v2
	v_mov_b32_e32 v30, v2
	v_mov_b32_e32 v31, v2
	v_mov_b32_e32 v32, v2
	v_mov_b32_e32 v33, v2
	v_mov_b32_e32 v34, v2
	v_mov_b32_e32 v35, v2
	v_mov_b32_e32 v36, v2
	v_mov_b32_e32 v37, v2
	v_mov_b32_e32 v38, v2
	v_mov_b32_e32 v39, v2
	v_mov_b32_e32 v40, v2
	v_mov_b32_e32 v41, v2
	v_mov_b32_e32 v42, v2
	v_mov_b32_e32 v43, v2
	v_mov_b32_e32 v44, v2
	v_mov_b32_e32 v45, v2
	v_mov_b32_e32 v46, v2
	v_mov_b32_e32 v47, v2
	v_mov_b32_e32 v48, v2
	v_mov_b32_e32 v49, v2
	v_mov_b32_e32 v50, v2
	v_mov_b32_e32 v51, v2
	v_mov_b32_e32 v52, v2
	v_mov_b32_e32 v53, v2
	v_mov_b32_e32 v54, v2
	v_mov_b32_e32 v55, v2
	v_mov_b32_e32 v56, v2
	v_mov_b32_e32 v57, v2
	v_mov_b32_e32 v58, v2
	v_mov_b32_e32 v59, v2
	v_mov_b32_e32 v60, v2
	v_mov_b32_e32 v61, v2
	v_mov_b32_e32 v62, v2
	v_mov_b32_e32 v63, v2
	v_mov_b32_e32 v64, v2
	v_mov_b32_e32 v65, v2
	v_mov_b32_e32 v66, v2
	v_mov_b32_e32 v67, v2
	v_mov_b32_e32 v68, v2
	v_mov_b32_e32 v69, v2
	v_mov_b32_e32 v70, v2
	v_mov_b32_e32 v71, v2
	v_mov_b32_e32 v72, v2
	v_mov_b32_e32 v73, v2
	v_mov_b32_e32 v74, v2
	v_mov_b32_e32 v75, v2
	v_mov_b32_e32 v76, v2
	v_mov_b32_e32 v77, v2
	v_mov_b32_e32 v78, v2
	v_mov_b32_e32 v79, v2
	v_mov_b32_e32 v80, v2
	v_mov_b32_e32 v81, v2
	v_mov_b32_e32 v82, v2
	v_mov_b32_e32 v83, v2
	v_mov_b32_e32 v84, v2
	v_mov_b32_e32 v85, v2
	v_mov_b32_e32 v86, v2
	v_mov_b32_e32 v87, v2
	v_mov_b32_e32 v88, v2
	v_mov_b32_e32 v89, v2
	v_mov_b32_e32 v90, v2
	v_mov_b32_e32 v91, v2
	v_mov_b32_e32 v92, v2
	v_mov_b32_e32 v93, v2
	v_mov_b32_e32 v94, v2
	v_mov_b32_e32 v95, v2
	v_mov_b32_e32 v96, v2
	v_mov_b32_e32 v97, v2
	v_mov_b32_e32 v98, v2
	v_mov_b32_e32 v99, v2
	v_mov_b32_e32 v100, v2
	v_mov_b32_e32 v101, v2
	v_mov_b32_e32 v102, v2
	v_mov_b32_e32 v103, v2
	v_mov_b32_e32 v104, v2
	v_mov_b32_e32 v105, v2
	v_mov_b32_e32 v106, v2
	v_mov_b32_e32 v107, v2
	v_mov_b32_e32 v108, v2
	v_mov_b32_e32 v109, v2
	v_mov_b32_e32 v110, v2
	v_mov_b32_e32 v111, v2
	v_mov_b32_e32 v112, v2
	v_mov_b32_e32 v113, v2
	v_mov_b32_e32 v114, v2
	v_mov_b32_e32 v115, v2
	v_mov_b32_e32 v116, v2
	v_mov_b32_e32 v117, v2
	v_mov_b32_e32 v118, v2
	v_mov_b32_e32 v119, v2
	v_mov_b32_e32 v120, v2
	v_mov_b32_e32 v121, v2
	v_mov_b32_e32 v122, v2
	v_mov_b32_e32 v123, v2
	v_mov_b32_e32 v124, v2
	v_mov_b32_e32 v125, v2
	v_mov_b32_e32 v126, v2
	v_mov_b32_e32 v127, v2
	v_mov_b32_e32 v128, v2
	v_mov_b32_e32 v129, v2

; DI unsigned pack2(float a, float b) { f2_t v = {a, b}; bf2_t r = __builtin_convertvector(v, bf2_t); return __builtin_bit_cast(unsigned, r); }
; template <int GP> DI void gemm_phase(const Params& p, int l, int which, char* smem, int wv) {
;     ...
;             if (ng) {
;               const float rinv = rinv8[ai * 4 + m];
; #pragma unroll
;               for (int e = 0; e < 8; ++e) { x1[e] = (x1[e] * rinv) * g1[e]; x2[e] = (x2[e] * rinv) * g2[e]; }
;     ...
;             u16* pp = p.P + (size_t)R * INW + n0 + head * 128;
;             u32x4 o;
;             o[0] = pack2(x1[0], x1[1]); o[1] = pack2(x1[2], x1[3]); o[2] = pack2(x1[4], x1[5]); o[3] = pack2(x1[6], x1[7]);
;             *(u32x4*)(pp + c1) = o;
;             o[0] = pack2(x2[0], x2[1]); o[1] = pack2(x2[2], x2[3]); o[2] = pack2(x2[4], x2[5]); o[3] = pack2(x2[6], x2[7]);
;             *(u32x4*)(pp + c2) = o;
.LBB0_296:
	v_readlane_b32 s0, v253, 21
	v_readlane_b32 s14, v253, 35
	v_readlane_b32 s15, v253, 36
	s_lshl_b32 s44, s24, 8
	v_readlane_b32 s1, v253, 22
	v_mov_b64_e32 v[176:177], s[14:15]
	s_ashr_i32 s45, s44, 31
	v_mad_i64_i32 v[176:177], s[0:1], v238, s85, v[176:177]
	v_lshl_add_u64 v[176:177], s[44:45], 1, v[176:177]
	s_lshl_b32 s18, s92, 1
	v_lshl_add_u64 v[180:181], v[176:177], 0, s[18:19]
	v_cvt_pk_bf16_f32 v176, v190, v191
	v_cvt_pk_bf16_f32 v177, v196, v197
	v_cvt_pk_bf16_f32 v178, v200, v201
	v_cvt_pk_bf16_f32 v179, v204, v205
	v_lshl_add_u64 v[180:181], v[144:145], 1, v[180:181]
	s_lshl_b32 s52, s37, 1
	s_mov_b32 s53, s19
	global_store_dwordx4 v[180:181], v[176:179], off nt
	v_lshl_add_u64 v[180:181], v[180:181], 0, s[52:53]
	s_and_b64 vcc, exec, s[96:97]
	v_cvt_pk_bf16_f32 v176, v192, v193
	v_cvt_pk_bf16_f32 v177, v198, v199
	v_cvt_pk_bf16_f32 v178, v202, v203
	v_cvt_pk_bf16_f32 v179, v206, v207
	v_readlane_b32 s2, v253, 23
	v_readlane_b32 s3, v253, 24
	v_readlane_b32 s4, v253, 25
	v_readlane_b32 s5, v253, 26
	v_readlane_b32 s6, v253, 27
	v_readlane_b32 s7, v253, 28
	v_readlane_b32 s8, v253, 29
	v_readlane_b32 s9, v253, 30
	v_readlane_b32 s10, v253, 31
	v_readlane_b32 s11, v253, 32
	v_readlane_b32 s12, v253, 33
	v_readlane_b32 s13, v253, 34
	global_store_dwordx4 v[180:181], v[176:179], off nt
	s_cbranch_vccnz .LBB0_345
	s_nop 0
	v_pk_mul_f32 v[176:177], v[54:55], v[174:175] op_sel_hi:[1,0]
	v_pk_mul_f32 v[178:179], v[22:23], v[174:175] op_sel_hi:[1,0]
	v_pk_mul_f32 v[198:199], v[176:177], v[146:147]
	v_pk_mul_f32 v[176:177], v[56:57], v[174:175] op_sel_hi:[1,0]
	v_pk_mul_f32 v[186:187], v[178:179], v[148:149]
	v_pk_mul_f32 v[178:179], v[24:25], v[174:175] op_sel_hi:[1,0]
	v_pk_mul_f32 v[190:191], v[176:177], v[150:151]
	v_pk_mul_f32 v[176:177], v[50:51], v[174:175] op_sel_hi:[1,0]
	v_pk_mul_f32 v[180:181], v[178:179], v[152:153]
	v_pk_mul_f32 v[178:179], v[18:19], v[174:175] op_sel_hi:[1,0]
	v_pk_mul_f32 v[182:183], v[176:177], v[154:155]
	v_pk_mul_f32 v[176:177], v[52:53], v[174:175] op_sel_hi:[1,0]
	v_pk_mul_f32 v[174:175], v[20:21], v[174:175] op_sel_hi:[1,0]
	v_pk_mul_f32 v[178:179], v[178:179], v[156:157]
	v_pk_mul_f32 v[176:177], v[176:177], v[158:159]
	v_pk_mul_f32 v[174:175], v[174:175], v[160:161]
	s_and_b64 vcc, exec, s[30:31]
	v_or_b32_e32 v165, 16, v238
	s_cbranch_vccnz .LBB0_299

; DI unsigned pack2(float a, float b) { f2_t v = {a, b}; bf2_t r = __builtin_convertvector(v, bf2_t); return __builtin_bit_cast(unsigned, r); }
; template <int GP> DI void gemm_phase(const Params& p, int l, int which, char* smem, int wv) {
;     ...
;             if (ng) {
;               const float rinv = rinv8[ai * 4 + m];
; #pragma unroll
;               for (int e = 0; e < 8; ++e) { x1[e] = (x1[e] * rinv) * g1[e]; x2[e] = (x2[e] * rinv) * g2[e]; }
;     ...
;             u16* pp = p.P + (size_t)R * INW + n0 + head * 128;
;             u32x4 o;
;             o[0] = pack2(x1[0], x1[1]); o[1] = pack2(x1[2], x1[3]); o[2] = pack2(x1[4], x1[5]); o[3] = pack2(x1[6], x1[7]);
;             *(u32x4*)(pp + c1) = o;
;             o[0] = pack2(x2[0], x2[1]); o[1] = pack2(x2[2], x2[3]); o[2] = pack2(x2[4], x2[5]); o[3] = pack2(x2[6], x2[7]);
;             *(u32x4*)(pp + c2) = o;
.LBB0_303:
	v_readlane_b32 s0, v253, 21
	v_readlane_b32 s14, v253, 35
	v_readlane_b32 s15, v253, 36
	v_readlane_b32 s1, v253, 22
	v_cvt_pk_bf16_f32 v176, v196, v197
	v_mov_b64_e32 v[174:175], s[14:15]
	v_mad_i64_i32 v[174:175], s[0:1], v165, s85, v[174:175]
	v_lshl_add_u64 v[174:175], s[44:45], 1, v[174:175]
	v_lshl_add_u64 v[178:179], v[174:175], 0, s[18:19]
	v_cvt_pk_bf16_f32 v174, v184, v185
	v_cvt_pk_bf16_f32 v175, v192, v193
	v_cvt_pk_bf16_f32 v177, v202, v203
	v_lshl_add_u64 v[178:179], v[144:145], 1, v[178:179]
	s_mov_b32 s53, s19
	global_store_dwordx4 v[178:179], v[174:177], off nt
	v_lshl_add_u64 v[178:179], v[178:179], 0, s[52:53]
	s_and_b64 vcc, exec, s[96:97]
	v_cvt_pk_bf16_f32 v174, v188, v189
	v_cvt_pk_bf16_f32 v175, v194, v195
	v_cvt_pk_bf16_f32 v176, v200, v201
	v_cvt_pk_bf16_f32 v177, v204, v205
	v_readlane_b32 s2, v253, 23
	v_readlane_b32 s3, v253, 24
	v_readlane_b32 s4, v253, 25
	v_readlane_b32 s5, v253, 26
	v_readlane_b32 s6, v253, 27
	v_readlane_b32 s7, v253, 28
	v_readlane_b32 s8, v253, 29
	v_readlane_b32 s9, v253, 30
	v_readlane_b32 s10, v253, 31
	v_readlane_b32 s11, v253, 32
	v_readlane_b32 s12, v253, 33
	v_readlane_b32 s13, v253, 34
	global_store_dwordx4 v[178:179], v[174:177], off nt
	s_cbranch_vccnz .LBB0_346
	s_nop 0
	v_pk_mul_f32 v[174:175], v[46:47], v[172:173] op_sel_hi:[1,0]
	v_pk_mul_f32 v[176:177], v[14:15], v[172:173] op_sel_hi:[1,0]
	v_pk_mul_f32 v[196:197], v[174:175], v[146:147]
	v_pk_mul_f32 v[174:175], v[48:49], v[172:173] op_sel_hi:[1,0]
	v_pk_mul_f32 v[184:185], v[176:177], v[148:149]
	v_pk_mul_f32 v[176:177], v[16:17], v[172:173] op_sel_hi:[1,0]
	v_pk_mul_f32 v[188:189], v[174:175], v[150:151]
	v_pk_mul_f32 v[174:175], v[42:43], v[172:173] op_sel_hi:[1,0]
	v_pk_mul_f32 v[178:179], v[176:177], v[152:153]
	v_pk_mul_f32 v[176:177], v[10:11], v[172:173] op_sel_hi:[1,0]
	v_pk_mul_f32 v[180:181], v[174:175], v[154:155]
	v_pk_mul_f32 v[174:175], v[44:45], v[172:173] op_sel_hi:[1,0]
	v_pk_mul_f32 v[172:173], v[12:13], v[172:173] op_sel_hi:[1,0]
	v_pk_mul_f32 v[176:177], v[176:177], v[156:157]
	v_pk_mul_f32 v[174:175], v[174:175], v[158:159]
	v_pk_mul_f32 v[172:173], v[172:173], v[160:161]
	s_and_b64 vcc, exec, s[30:31]
	v_or_b32_e32 v165, 32, v238
	s_cbranch_vccnz .LBB0_306

; DI unsigned pack2(float a, float b) { f2_t v = {a, b}; bf2_t r = __builtin_convertvector(v, bf2_t); return __builtin_bit_cast(unsigned, r); }
; template <int GP> DI void gemm_phase(const Params& p, int l, int which, char* smem, int wv) {
;     ...
;             if (ng) {
;               const float rinv = rinv8[ai * 4 + m];
; #pragma unroll
;               for (int e = 0; e < 8; ++e) { x1[e] = (x1[e] * rinv) * g1[e]; x2[e] = (x2[e] * rinv) * g2[e]; }
;     ...
;             u16* pp = p.P + (size_t)R * INW + n0 + head * 128;
;             u32x4 o;
;             o[0] = pack2(x1[0], x1[1]); o[1] = pack2(x1[2], x1[3]); o[2] = pack2(x1[4], x1[5]); o[3] = pack2(x1[6], x1[7]);
;             *(u32x4*)(pp + c1) = o;
;             o[0] = pack2(x2[0], x2[1]); o[1] = pack2(x2[2], x2[3]); o[2] = pack2(x2[4], x2[5]); o[3] = pack2(x2[6], x2[7]);
;             *(u32x4*)(pp + c2) = o;
.LBB0_310:
	v_readlane_b32 s0, v253, 21
	v_readlane_b32 s14, v253, 35
	v_readlane_b32 s15, v253, 36
	v_readlane_b32 s1, v253, 22
	v_cvt_pk_bf16_f32 v174, v194, v195
	v_mov_b64_e32 v[172:173], s[14:15]
	v_mad_i64_i32 v[172:173], s[0:1], v165, s85, v[172:173]
	v_lshl_add_u64 v[172:173], s[44:45], 1, v[172:173]
	v_lshl_add_u64 v[176:177], v[172:173], 0, s[18:19]
	v_cvt_pk_bf16_f32 v172, v182, v183
	v_cvt_pk_bf16_f32 v173, v190, v191
	v_cvt_pk_bf16_f32 v175, v200, v201
	v_lshl_add_u64 v[176:177], v[144:145], 1, v[176:177]
	s_mov_b32 s53, s19
	global_store_dwordx4 v[176:177], v[172:175], off nt
	v_lshl_add_u64 v[176:177], v[176:177], 0, s[52:53]
	s_and_b64 vcc, exec, s[96:97]
	v_cvt_pk_bf16_f32 v172, v186, v187
	v_cvt_pk_bf16_f32 v173, v192, v193
	v_cvt_pk_bf16_f32 v174, v198, v199
	v_cvt_pk_bf16_f32 v175, v202, v203
	v_readlane_b32 s2, v253, 23
	v_readlane_b32 s3, v253, 24
	v_readlane_b32 s4, v253, 25
	v_readlane_b32 s5, v253, 26
	v_readlane_b32 s6, v253, 27
	v_readlane_b32 s7, v253, 28
	v_readlane_b32 s8, v253, 29
	v_readlane_b32 s9, v253, 30
	v_readlane_b32 s10, v253, 31
	v_readlane_b32 s11, v253, 32
	v_readlane_b32 s12, v253, 33
	v_readlane_b32 s13, v253, 34
	global_store_dwordx4 v[176:177], v[172:175], off nt
	s_cbranch_vccnz .LBB0_347
	s_nop 0
	v_pk_mul_f32 v[172:173], v[38:39], v[170:171] op_sel_hi:[1,0]
	v_pk_mul_f32 v[174:175], v[6:7], v[170:171] op_sel_hi:[1,0]
	v_pk_mul_f32 v[194:195], v[172:173], v[146:147]
	v_pk_mul_f32 v[172:173], v[40:41], v[170:171] op_sel_hi:[1,0]
	v_pk_mul_f32 v[182:183], v[174:175], v[148:149]
	v_pk_mul_f32 v[174:175], v[8:9], v[170:171] op_sel_hi:[1,0]
	v_pk_mul_f32 v[186:187], v[172:173], v[150:151]
	v_pk_mul_f32 v[172:173], v[34:35], v[170:171] op_sel_hi:[1,0]
	v_pk_mul_f32 v[176:177], v[174:175], v[152:153]
	v_pk_mul_f32 v[174:175], v[2:3], v[170:171] op_sel_hi:[1,0]
	v_pk_mul_f32 v[178:179], v[172:173], v[154:155]
	v_pk_mul_f32 v[172:173], v[36:37], v[170:171] op_sel_hi:[1,0]
	v_pk_mul_f32 v[170:171], v[4:5], v[170:171] op_sel_hi:[1,0]
	v_pk_mul_f32 v[174:175], v[174:175], v[156:157]
	v_pk_mul_f32 v[172:173], v[172:173], v[158:159]
	v_pk_mul_f32 v[170:171], v[170:171], v[160:161]
	s_and_b64 vcc, exec, s[30:31]
	v_or_b32_e32 v165, 48, v238
	s_cbranch_vccnz .LBB0_313

; DI unsigned pack2(float a, float b) { f2_t v = {a, b}; bf2_t r = __builtin_convertvector(v, bf2_t); return __builtin_bit_cast(unsigned, r); }
; template <int GP> DI void gemm_phase(const Params& p, int l, int which, char* smem, int wv) {
;     ...
;             if (ng) {
;               const float rinv = rinv8[ai * 4 + m];
; #pragma unroll
;               for (int e = 0; e < 8; ++e) { x1[e] = (x1[e] * rinv) * g1[e]; x2[e] = (x2[e] * rinv) * g2[e]; }
;     ...
;             u16* pp = p.P + (size_t)R * INW + n0 + head * 128;
;             u32x4 o;
;             o[0] = pack2(x1[0], x1[1]); o[1] = pack2(x1[2], x1[3]); o[2] = pack2(x1[4], x1[5]); o[3] = pack2(x1[6], x1[7]);
;             *(u32x4*)(pp + c1) = o;
;             o[0] = pack2(x2[0], x2[1]); o[1] = pack2(x2[2], x2[3]); o[2] = pack2(x2[4], x2[5]); o[3] = pack2(x2[6], x2[7]);
;             *(u32x4*)(pp + c2) = o;
.LBB0_317:
	v_readlane_b32 s0, v253, 21
	v_readlane_b32 s14, v253, 35
	v_readlane_b32 s15, v253, 36
	v_readlane_b32 s1, v253, 22
	v_cvt_pk_bf16_f32 v172, v192, v193
	v_mov_b64_e32 v[170:171], s[14:15]
	v_mad_i64_i32 v[170:171], s[0:1], v165, s85, v[170:171]
	v_lshl_add_u64 v[170:171], s[44:45], 1, v[170:171]
	v_lshl_add_u64 v[174:175], v[170:171], 0, s[18:19]
	v_cvt_pk_bf16_f32 v170, v180, v181
	v_cvt_pk_bf16_f32 v171, v188, v189
	v_cvt_pk_bf16_f32 v173, v198, v199
	v_lshl_add_u64 v[174:175], v[144:145], 1, v[174:175]
	s_mov_b32 s53, s19
	global_store_dwordx4 v[174:175], v[170:173], off nt
	v_lshl_add_u64 v[174:175], v[174:175], 0, s[52:53]
	s_and_b64 vcc, exec, s[96:97]
	v_cvt_pk_bf16_f32 v170, v184, v185
	v_cvt_pk_bf16_f32 v171, v190, v191
	v_cvt_pk_bf16_f32 v172, v196, v197
	v_cvt_pk_bf16_f32 v173, v200, v201
	v_readlane_b32 s2, v253, 23
	v_readlane_b32 s3, v253, 24
	v_readlane_b32 s4, v253, 25
	v_readlane_b32 s5, v253, 26
	v_readlane_b32 s6, v253, 27
	v_readlane_b32 s7, v253, 28
	v_readlane_b32 s8, v253, 29
	v_readlane_b32 s9, v253, 30
	v_readlane_b32 s10, v253, 31
	v_readlane_b32 s11, v253, 32
	v_readlane_b32 s12, v253, 33
	v_readlane_b32 s13, v253, 34
	global_store_dwordx4 v[174:175], v[170:173], off nt
	s_cbranch_vccnz .LBB0_348
	s_nop 0
	v_pk_mul_f32 v[170:171], v[66:67], v[168:169] op_sel_hi:[1,0]
	v_pk_mul_f32 v[172:173], v[98:99], v[168:169] op_sel_hi:[1,0]
	v_pk_mul_f32 v[192:193], v[170:171], v[146:147]
	v_pk_mul_f32 v[170:171], v[68:69], v[168:169] op_sel_hi:[1,0]
	v_pk_mul_f32 v[180:181], v[172:173], v[148:149]
	v_pk_mul_f32 v[172:173], v[100:101], v[168:169] op_sel_hi:[1,0]
	v_pk_mul_f32 v[184:185], v[170:171], v[150:151]
	v_pk_mul_f32 v[170:171], v[70:71], v[168:169] op_sel_hi:[1,0]
	v_pk_mul_f32 v[174:175], v[172:173], v[152:153]
	v_pk_mul_f32 v[172:173], v[102:103], v[168:169] op_sel_hi:[1,0]
	v_pk_mul_f32 v[176:177], v[170:171], v[154:155]
	v_pk_mul_f32 v[170:171], v[72:73], v[168:169] op_sel_hi:[1,0]
	v_pk_mul_f32 v[168:169], v[104:105], v[168:169] op_sel_hi:[1,0]
	v_pk_mul_f32 v[172:173], v[172:173], v[156:157]
	v_pk_mul_f32 v[170:171], v[170:171], v[158:159]
	v_pk_mul_f32 v[168:169], v[168:169], v[160:161]
	s_and_b64 vcc, exec, s[30:31]
	v_add_u32_e32 v165, 0x80, v238
	s_cbranch_vccnz .LBB0_320

; DI unsigned pack2(float a, float b) { f2_t v = {a, b}; bf2_t r = __builtin_convertvector(v, bf2_t); return __builtin_bit_cast(unsigned, r); }
; DI float fexp2(float x) { return __builtin_amdgcn_exp2f(x); }
; template <int GP> DI void gemm_phase(const Params& p, int l, int which, char* smem, int wv) {
;     ...
;             if (ng) {
;               const float rinv = rinv8[ai * 4 + m];
; #pragma unroll
;               for (int e = 0; e < 8; ++e) { x1[e] = (x1[e] * rinv) * g1[e]; x2[e] = (x2[e] * rinv) * g2[e]; }
;             }
;             if (rope && !isctx) {
;               const int tt = (R % TPB) - 256;
;               const float pos = (float)(use_col ? (tt & 63) : (tt >> 6));
; #pragma unroll
;               for (int e = 0; e < 8; ++e) {
;                 float rev = pos * frev[e];
;                 rev = rev - floorf(rev);
;                 const float cs = __builtin_amdgcn_cosf(rev), sn = __builtin_amdgcn_sinf(rev);
;                 const float a = x1[e], bq = x2[e];
;                 x1[e] = a * cs - bq * sn; x2[e] = bq * cs + a * sn;
;               }
;             }
;             if (silu) {
; #pragma unroll
;               for (int e = 0; e < 8; ++e) { x1[e] = x1[e] * __builtin_amdgcn_rcpf(1.f + fexp2(-LOG2E * x1[e])); x2[e] = x2[e] * __builtin_amdgcn_rcpf(1.f + fexp2(-LOG2E * x2[e])); }
;             } else {
; #pragma unroll
;               for (int e = 0; e < 8; ++e) { x1[e] *= qmul; x2[e] *= qmul; }
;             }
;             u16* pp = p.P + (size_t)R * INW + n0 + head * 128;
;             u32x4 o;
;             o[0] = pack2(x1[0], x1[1]); o[1] = pack2(x1[2], x1[3]); o[2] = pack2(x1[4], x1[5]); o[3] = pack2(x1[6], x1[7]);
;             *(u32x4*)(pp + c1) = o;
;             o[0] = pack2(x2[0], x2[1]); o[1] = pack2(x2[2], x2[3]); o[2] = pack2(x2[4], x2[5]); o[3] = pack2(x2[6], x2[7]);
;             *(u32x4*)(pp + c2) = o;
.LBB0_324:
	v_readlane_b32 s0, v253, 21
	v_readlane_b32 s14, v253, 35
	v_readlane_b32 s15, v253, 36
	v_readlane_b32 s1, v253, 22
	v_cvt_pk_bf16_f32 v170, v190, v191
	v_mov_b64_e32 v[168:169], s[14:15]
	v_mad_i64_i32 v[168:169], s[0:1], v165, s85, v[168:169]
	v_lshl_add_u64 v[168:169], s[44:45], 1, v[168:169]
	v_lshl_add_u64 v[172:173], v[168:169], 0, s[18:19]
	v_cvt_pk_bf16_f32 v168, v178, v179
	v_cvt_pk_bf16_f32 v169, v186, v187
	v_cvt_pk_bf16_f32 v171, v196, v197
	v_lshl_add_u64 v[172:173], v[144:145], 1, v[172:173]
	s_mov_b32 s53, s19
	global_store_dwordx4 v[172:173], v[168:171], off nt
	v_lshl_add_u64 v[172:173], v[172:173], 0, s[52:53]
	s_and_b64 vcc, exec, s[96:97]
	v_cvt_pk_bf16_f32 v168, v182, v183
	v_cvt_pk_bf16_f32 v169, v188, v189
	v_cvt_pk_bf16_f32 v170, v194, v195
	v_cvt_pk_bf16_f32 v171, v198, v199
	v_readlane_b32 s2, v253, 23
	v_readlane_b32 s3, v253, 24
	v_readlane_b32 s4, v253, 25
	v_readlane_b32 s5, v253, 26
	v_readlane_b32 s6, v253, 27
	v_readlane_b32 s7, v253, 28
	v_readlane_b32 s8, v253, 29
	v_readlane_b32 s9, v253, 30
	v_readlane_b32 s10, v253, 31
	v_readlane_b32 s11, v253, 32
	v_readlane_b32 s12, v253, 33
	v_readlane_b32 s13, v253, 34
	global_store_dwordx4 v[172:173], v[168:171], off nt
	s_cbranch_vccnz .LBB0_349
	s_nop 0
	v_pk_mul_f32 v[168:169], v[74:75], v[166:167] op_sel_hi:[1,0]
	v_pk_mul_f32 v[170:171], v[106:107], v[166:167] op_sel_hi:[1,0]
	v_pk_mul_f32 v[190:191], v[168:169], v[146:147]
	v_pk_mul_f32 v[168:169], v[76:77], v[166:167] op_sel_hi:[1,0]
	v_pk_mul_f32 v[178:179], v[170:171], v[148:149]
	v_pk_mul_f32 v[170:171], v[108:109], v[166:167] op_sel_hi:[1,0]
	v_pk_mul_f32 v[182:183], v[168:169], v[150:151]
	v_pk_mul_f32 v[168:169], v[78:79], v[166:167] op_sel_hi:[1,0]
	v_pk_mul_f32 v[172:173], v[170:171], v[152:153]
	v_pk_mul_f32 v[170:171], v[110:111], v[166:167] op_sel_hi:[1,0]
	v_pk_mul_f32 v[174:175], v[168:169], v[154:155]
	v_pk_mul_f32 v[168:169], v[80:81], v[166:167] op_sel_hi:[1,0]
	v_pk_mul_f32 v[166:167], v[112:113], v[166:167] op_sel_hi:[1,0]
	v_pk_mul_f32 v[170:171], v[170:171], v[156:157]
	v_pk_mul_f32 v[168:169], v[168:169], v[158:159]
	v_pk_mul_f32 v[166:167], v[166:167], v[160:161]
	s_and_b64 vcc, exec, s[30:31]
	v_add_u32_e32 v165, 0x90, v238
	s_cbranch_vccnz .LBB0_327

; DI unsigned pack2(float a, float b) { f2_t v = {a, b}; bf2_t r = __builtin_convertvector(v, bf2_t); return __builtin_bit_cast(unsigned, r); }
; DI float fexp2(float x) { return __builtin_amdgcn_exp2f(x); }
; template <int GP> DI void gemm_phase(const Params& p, int l, int which, char* smem, int wv) {
;     ...
;             if (ng) {
;               const float rinv = rinv8[ai * 4 + m];
; #pragma unroll
;               for (int e = 0; e < 8; ++e) { x1[e] = (x1[e] * rinv) * g1[e]; x2[e] = (x2[e] * rinv) * g2[e]; }
;             }
;             if (rope && !isctx) {
;               const int tt = (R % TPB) - 256;
;               const float pos = (float)(use_col ? (tt & 63) : (tt >> 6));
; #pragma unroll
;               for (int e = 0; e < 8; ++e) {
;                 float rev = pos * frev[e];
;                 rev = rev - floorf(rev);
;                 const float cs = __builtin_amdgcn_cosf(rev), sn = __builtin_amdgcn_sinf(rev);
;                 const float a = x1[e], bq = x2[e];
;                 x1[e] = a * cs - bq * sn; x2[e] = bq * cs + a * sn;
;               }
;             }
;             if (silu) {
; #pragma unroll
;               for (int e = 0; e < 8; ++e) { x1[e] = x1[e] * __builtin_amdgcn_rcpf(1.f + fexp2(-LOG2E * x1[e])); x2[e] = x2[e] * __builtin_amdgcn_rcpf(1.f + fexp2(-LOG2E * x2[e])); }
;             } else {
; #pragma unroll
;               for (int e = 0; e < 8; ++e) { x1[e] *= qmul; x2[e] *= qmul; }
;             }
;             u16* pp = p.P + (size_t)R * INW + n0 + head * 128;
;             u32x4 o;
;             o[0] = pack2(x1[0], x1[1]); o[1] = pack2(x1[2], x1[3]); o[2] = pack2(x1[4], x1[5]); o[3] = pack2(x1[6], x1[7]);
;             *(u32x4*)(pp + c1) = o;
;             o[0] = pack2(x2[0], x2[1]); o[1] = pack2(x2[2], x2[3]); o[2] = pack2(x2[4], x2[5]); o[3] = pack2(x2[6], x2[7]);
;             *(u32x4*)(pp + c2) = o;
.LBB0_331:
	v_readlane_b32 s0, v253, 21
	v_readlane_b32 s14, v253, 35
	v_readlane_b32 s15, v253, 36
	v_readlane_b32 s1, v253, 22
	v_cvt_pk_bf16_f32 v168, v188, v189
	v_mov_b64_e32 v[166:167], s[14:15]
	v_mad_i64_i32 v[166:167], s[0:1], v165, s85, v[166:167]
	v_lshl_add_u64 v[166:167], s[44:45], 1, v[166:167]
	v_lshl_add_u64 v[170:171], v[166:167], 0, s[18:19]
	v_cvt_pk_bf16_f32 v166, v176, v177
	v_cvt_pk_bf16_f32 v167, v184, v185
	v_cvt_pk_bf16_f32 v169, v194, v195
	v_lshl_add_u64 v[170:171], v[144:145], 1, v[170:171]
	s_mov_b32 s53, s19
	global_store_dwordx4 v[170:171], v[166:169], off nt
	v_lshl_add_u64 v[170:171], v[170:171], 0, s[52:53]
	s_and_b64 vcc, exec, s[96:97]
	v_cvt_pk_bf16_f32 v166, v180, v181
	v_cvt_pk_bf16_f32 v167, v186, v187
	v_cvt_pk_bf16_f32 v168, v192, v193
	v_cvt_pk_bf16_f32 v169, v196, v197
	v_readlane_b32 s2, v253, 23
	v_readlane_b32 s3, v253, 24
	v_readlane_b32 s4, v253, 25
	v_readlane_b32 s5, v253, 26
	v_readlane_b32 s6, v253, 27
	v_readlane_b32 s7, v253, 28
	v_readlane_b32 s8, v253, 29
	v_readlane_b32 s9, v253, 30
	v_readlane_b32 s10, v253, 31
	v_readlane_b32 s11, v253, 32
	v_readlane_b32 s12, v253, 33
	v_readlane_b32 s13, v253, 34
	global_store_dwordx4 v[170:171], v[166:169], off nt
	s_cbranch_vccnz .LBB0_350
	s_nop 0
	v_pk_mul_f32 v[166:167], v[82:83], v[164:165] op_sel_hi:[1,0]
	v_pk_mul_f32 v[168:169], v[114:115], v[164:165] op_sel_hi:[1,0]
	v_pk_mul_f32 v[188:189], v[166:167], v[146:147]
	v_pk_mul_f32 v[166:167], v[84:85], v[164:165] op_sel_hi:[1,0]
	v_pk_mul_f32 v[176:177], v[168:169], v[148:149]
	v_pk_mul_f32 v[168:169], v[116:117], v[164:165] op_sel_hi:[1,0]
	v_pk_mul_f32 v[180:181], v[166:167], v[150:151]
	v_pk_mul_f32 v[166:167], v[86:87], v[164:165] op_sel_hi:[1,0]
	v_pk_mul_f32 v[170:171], v[168:169], v[152:153]
	v_pk_mul_f32 v[168:169], v[118:119], v[164:165] op_sel_hi:[1,0]
	v_pk_mul_f32 v[172:173], v[166:167], v[154:155]
	v_pk_mul_f32 v[166:167], v[88:89], v[164:165] op_sel_hi:[1,0]
	v_pk_mul_f32 v[164:165], v[120:121], v[164:165] op_sel_hi:[1,0]
	v_pk_mul_f32 v[168:169], v[168:169], v[156:157]
	v_pk_mul_f32 v[166:167], v[166:167], v[158:159]
	v_pk_mul_f32 v[164:165], v[164:165], v[160:161]
	s_and_b64 vcc, exec, s[30:31]
	v_add_u32_e32 v196, 0xa0, v238
	s_cbranch_vccnz .LBB0_334

; DI unsigned pack2(float a, float b) { f2_t v = {a, b}; bf2_t r = __builtin_convertvector(v, bf2_t); return __builtin_bit_cast(unsigned, r); }
; DI float fexp2(float x) { return __builtin_amdgcn_exp2f(x); }
; template <int GP> DI void gemm_phase(const Params& p, int l, int which, char* smem, int wv) {
;     ...
;             if (ng) {
;               const float rinv = rinv8[ai * 4 + m];
; #pragma unroll
;               for (int e = 0; e < 8; ++e) { x1[e] = (x1[e] * rinv) * g1[e]; x2[e] = (x2[e] * rinv) * g2[e]; }
;             }
;             if (rope && !isctx) {
;               const int tt = (R % TPB) - 256;
;               const float pos = (float)(use_col ? (tt & 63) : (tt >> 6));
; #pragma unroll
;               for (int e = 0; e < 8; ++e) {
;                 float rev = pos * frev[e];
;                 rev = rev - floorf(rev);
;                 const float cs = __builtin_amdgcn_cosf(rev), sn = __builtin_amdgcn_sinf(rev);
;                 const float a = x1[e], bq = x2[e];
;                 x1[e] = a * cs - bq * sn; x2[e] = bq * cs + a * sn;
;               }
;             }
;             if (silu) {
; #pragma unroll
;               for (int e = 0; e < 8; ++e) { x1[e] = x1[e] * __builtin_amdgcn_rcpf(1.f + fexp2(-LOG2E * x1[e])); x2[e] = x2[e] * __builtin_amdgcn_rcpf(1.f + fexp2(-LOG2E * x2[e])); }
;             } else {
; #pragma unroll
;               for (int e = 0; e < 8; ++e) { x1[e] *= qmul; x2[e] *= qmul; }
;             }
;             u16* pp = p.P + (size_t)R * INW + n0 + head * 128;
;             u32x4 o;
;             o[0] = pack2(x1[0], x1[1]); o[1] = pack2(x1[2], x1[3]); o[2] = pack2(x1[4], x1[5]); o[3] = pack2(x1[6], x1[7]);
;             *(u32x4*)(pp + c1) = o;
;             o[0] = pack2(x2[0], x2[1]); o[1] = pack2(x2[2], x2[3]); o[2] = pack2(x2[4], x2[5]); o[3] = pack2(x2[6], x2[7]);
;             *(u32x4*)(pp + c2) = o;
.LBB0_338:
	v_readlane_b32 s0, v253, 21
	v_readlane_b32 s14, v253, 35
	v_readlane_b32 s15, v253, 36
	v_readlane_b32 s1, v253, 22
	v_cvt_pk_bf16_f32 v166, v186, v187
	v_mov_b64_e32 v[164:165], s[14:15]
	v_mad_i64_i32 v[164:165], s[0:1], v196, s85, v[164:165]
	v_lshl_add_u64 v[164:165], s[44:45], 1, v[164:165]
	v_lshl_add_u64 v[168:169], v[164:165], 0, s[18:19]
	v_cvt_pk_bf16_f32 v164, v174, v175
	v_cvt_pk_bf16_f32 v165, v182, v183
	v_cvt_pk_bf16_f32 v167, v192, v193
	v_lshl_add_u64 v[168:169], v[144:145], 1, v[168:169]
	s_mov_b32 s53, s19
	global_store_dwordx4 v[168:169], v[164:167], off nt
	v_lshl_add_u64 v[168:169], v[168:169], 0, s[52:53]
	s_and_b64 vcc, exec, s[96:97]
	v_cvt_pk_bf16_f32 v164, v178, v179
	v_cvt_pk_bf16_f32 v165, v184, v185
	v_cvt_pk_bf16_f32 v166, v190, v191
	v_cvt_pk_bf16_f32 v167, v194, v195
	v_readlane_b32 s2, v253, 23
	v_readlane_b32 s3, v253, 24
	v_readlane_b32 s4, v253, 25
	v_readlane_b32 s5, v253, 26
	v_readlane_b32 s6, v253, 27
	v_readlane_b32 s7, v253, 28
	v_readlane_b32 s8, v253, 29
	v_readlane_b32 s9, v253, 30
	v_readlane_b32 s10, v253, 31
	v_readlane_b32 s11, v253, 32
	v_readlane_b32 s12, v253, 33
	v_readlane_b32 s13, v253, 34
	global_store_dwordx4 v[168:169], v[164:167], off nt
	s_cbranch_vccnz .LBB0_351
	s_nop 0
	v_pk_mul_f32 v[164:165], v[90:91], v[162:163] op_sel_hi:[1,0]
	v_pk_mul_f32 v[166:167], v[122:123], v[162:163] op_sel_hi:[1,0]
	v_pk_mul_f32 v[170:171], v[164:165], v[146:147]
	v_pk_mul_f32 v[164:165], v[166:167], v[148:149]
	v_pk_mul_f32 v[146:147], v[92:93], v[162:163] op_sel_hi:[1,0]
	v_pk_mul_f32 v[148:149], v[124:125], v[162:163] op_sel_hi:[1,0]
	v_pk_mul_f32 v[166:167], v[146:147], v[150:151]
	v_pk_mul_f32 v[152:153], v[148:149], v[152:153]
	v_pk_mul_f32 v[146:147], v[94:95], v[162:163] op_sel_hi:[1,0]
	v_pk_mul_f32 v[148:149], v[126:127], v[162:163] op_sel_hi:[1,0]
	v_pk_mul_f32 v[154:155], v[146:147], v[154:155]
	v_pk_mul_f32 v[150:151], v[148:149], v[156:157]
	v_pk_mul_f32 v[146:147], v[96:97], v[162:163] op_sel_hi:[1,0]
	v_pk_mul_f32 v[156:157], v[128:129], v[162:163] op_sel_hi:[1,0]
	v_pk_mul_f32 v[148:149], v[146:147], v[158:159]
	v_pk_mul_f32 v[146:147], v[156:157], v[160:161]
	s_and_b64 vcc, exec, s[30:31]
	v_add_u32_e32 v178, 0xb0, v238
	s_cbranch_vccnz .LBB0_341
